# v38 + conflict-free LDS swizzle + software-pipelined GEMM K-loops
# speedup vs baseline: 1.0141x; 1.0104x over previous
; template <int MODE, bool SWAP, int MT>
; DI void gemm_tile(const int wv_, const Params& p, const u16* __restrict__ A, const u16* __restrict__ Bt, int brow, int bcol, char* smem, const float* gnext) {
;     ...
;   const int ra = tid >> 2, cb = (tid & 3) * 8;
;   const u16* ga0 = A + (size_t)(brow + ra) * 1024 + cb;
;   const u16* ga1 = A + (size_t)(brow + 128 + ra) * 1024 + cb;
;   const u16* gb0 = Bt + (size_t)(bcol + ra) * 1024 + cb;
;   auto stage = [&](int t, int buf) {
;     char* sA = smem + buf * 24576; char* sB = sA + 16384;
;     if (MT >= 2 || tid < 256) __builtin_amdgcn_global_load_lds((const unsigned*)(ga0 + t * 32), (unsigned*)(sA + tid * 16), 16, 0, 0);
;     if (MT == 4) __builtin_amdgcn_global_load_lds((const unsigned*)(ga1 + t * 32), (unsigned*)(sA + 8192 + tid * 16), 16, 0, 0);
;     __builtin_amdgcn_global_load_lds((const unsigned*)(gb0 + t * 32), (unsigned*)(sB + tid * 16), 16, 0, 0);
;   };
;   stage(0, 0);
;   for (int t = 0; t < 32; ++t) {
;     asm volatile("s_waitcnt vmcnt(0)" ::: "memory");
;     __syncthreads();
;     if (t + 1 < 32) stage(t + 1, (t + 1) & 1);
;     const char* sA = smem + (t & 1) * 24576; const char* sB = sA + 16384;
.LBB0_84:
	s_mul_hi_i32 s0, s14, 0x92492493
	s_add_i32 s0, s0, s14
	s_lshr_b32 s1, s0, 31
	s_ashr_i32 s0, s0, 4
	s_add_i32 s19, s0, s1
	s_mul_i32 s0, s19, 0xffffffe4
	s_add_i32 s0, s0, s14
	s_and_b32 s1, s0, -4
	s_lshl_b32 s18, s19, 8
	s_lshl_b32 s15, s0, 7
	s_cmp_lg_u32 s1, 20
	s_mov_b64 s[0:1], -1
	s_mulk_i32 s19, 0xe00
	s_cbranch_scc0 .LBB0_88
	s_mov_b32 s1, 0
	v_readlane_b32 s20, v127, 0
	v_mbcnt_lo_u32_b32 v0, -1, s1
	v_mbcnt_hi_u32_b32 v0, -1, v0
	v_add_u32_e32 v12, s33, v0
	s_mov_b32 s1, s16
	v_ashrrev_i32_e32 v13, 2, v12
	v_add_u32_e32 v0, s18, v13
	s_mov_b32 s1, s17
	v_ashrrev_i32_e32 v1, 31, v0
	v_lshlrev_b64 v[4:5], 11, v[0:1]
	v_readlane_b32 s21, v127, 1
	v_lshlrev_b32_e32 v76, 4, v12
	v_lshrrev_b32_e32 v2, 8, v76
	v_sub_u32_e32 v2, 0, v2
	v_lshlrev_b32_e32 v2, 4, v2
	v_xor_b32_e32 v2, v2, v76
	v_and_b32_e32 v2, 48, v2
	v_lshl_add_u64 v[6:7], s[20:21], 0, v[4:5]
	v_add_u32_e32 v0, 0x80, v0
	v_readfirstlane_b32 s1, v76
	v_lshl_add_u64 v[6:7], v[6:7], 0, v[2:3]
	v_ashrrev_i32_e32 v1, 31, v0
	s_mov_b32 m0, s1
	v_lshlrev_b64 v[8:9], 11, v[0:1]
	global_load_lds_dwordx4 v[6:7], off
	v_add_u32_e32 v6, 0x2000, v76
	v_lshl_add_u64 v[0:1], s[20:21], 0, v[8:9]
	v_add_u32_e32 v10, s15, v13
	v_readfirstlane_b32 s1, v6
	v_lshl_add_u64 v[0:1], v[0:1], 0, v[2:3]
	v_ashrrev_i32_e32 v11, 31, v10
	s_mov_b32 m0, s1
	v_lshlrev_b64 v[10:11], 11, v[10:11]
	global_load_lds_dwordx4 v[0:1], off
	v_add_u32_e32 v0, 0x4000, v76
	v_lshl_add_u64 v[10:11], s[2:3], 0, v[10:11]
	v_readfirstlane_b32 s1, v0
	v_lshl_add_u64 v[10:11], v[10:11], 0, v[2:3]
	s_mov_b32 m0, s1
	v_and_b32_e32 v74, 15, v12
	global_load_lds_dwordx4 v[10:11], off
	v_readlane_b32 s20, v127, 22
	v_bfe_u32 v72, v12, 6, 1
	v_ashrrev_i32_e32 v73, 7, v12
	v_lshlrev_b32_e32 v0, 6, v74
	v_or_b32_e32 v4, v4, v2
	v_readlane_b32 s21, v127, 23
	v_lshl_or_b32 v78, v72, 12, v0
	v_lshl_or_b32 v79, v73, 12, v0
	v_lshl_add_u64 v[0:1], s[20:21], 0, v[4:5]
	v_add_u32_e32 v4, s12, v13
	v_subrev_u32_e32 v4, s19, v4
	v_ashrrev_i32_e32 v5, 31, v4
	v_lshlrev_b64 v[4:5], 11, v[4:5]
	v_or_b32_e32 v4, v4, v2
	v_bfe_u32 v75, v12, 4, 2
	v_or_b32_e32 v8, v8, v2
	v_lshl_add_u64 v[70:71], s[4:5], 0, v[4:5]
	v_mov_b32_e32 v4, 0
	s_mov_b32 s0, 0
	v_lshrrev_b32_e32 v77, 2, v74
	v_sub_u32_e32 v77, 0, v77
	v_xor_b32_e32 v77, v77, v75
	v_and_b32_e32 v77, 3, v77
	v_lshlrev_b32_e32 v77, 4, v77
	v_lshl_add_u64 v[68:69], s[20:21], 0, v[8:9]
	v_mov_b32_e32 v5, v4
	v_mov_b32_e32 v6, v4
	v_mov_b32_e32 v7, v4
	v_mov_b32_e32 v8, v4
	v_mov_b32_e32 v9, v4
	v_mov_b32_e32 v10, v4
	v_mov_b32_e32 v11, v4
	v_mov_b32_e32 v12, v4
	v_mov_b32_e32 v13, v4
	v_mov_b32_e32 v14, v4
	v_mov_b32_e32 v15, v4
	v_mov_b32_e32 v16, v4
	v_mov_b32_e32 v17, v4
	v_mov_b32_e32 v18, v4
	v_mov_b32_e32 v19, v4
	v_mov_b32_e32 v20, v4
	v_mov_b32_e32 v21, v4
	v_mov_b32_e32 v22, v4
	v_mov_b32_e32 v23, v4
	v_mov_b32_e32 v24, v4
	v_mov_b32_e32 v25, v4
	v_mov_b32_e32 v26, v4
	v_mov_b32_e32 v27, v4
	v_mov_b32_e32 v28, v4
	v_mov_b32_e32 v29, v4
	v_mov_b32_e32 v30, v4
	v_mov_b32_e32 v31, v4
	v_mov_b32_e32 v32, v4
	v_mov_b32_e32 v33, v4
	v_mov_b32_e32 v34, v4
	v_mov_b32_e32 v35, v4
	v_mov_b32_e32 v44, v4
	v_mov_b32_e32 v45, v4
	v_mov_b32_e32 v46, v4
	v_mov_b32_e32 v47, v4
	v_mov_b32_e32 v36, v4
	v_mov_b32_e32 v37, v4
	v_mov_b32_e32 v38, v4
	v_mov_b32_e32 v39, v4
	v_mov_b32_e32 v40, v4
	v_mov_b32_e32 v41, v4
	v_mov_b32_e32 v42, v4
	v_mov_b32_e32 v43, v4
	v_mov_b32_e32 v48, v4
	v_mov_b32_e32 v49, v4
	v_mov_b32_e32 v50, v4
	v_mov_b32_e32 v51, v4
	v_mov_b32_e32 v52, v4
	v_mov_b32_e32 v53, v4
	v_mov_b32_e32 v54, v4
	v_mov_b32_e32 v55, v4
	v_mov_b32_e32 v56, v4
	v_mov_b32_e32 v57, v4
	v_mov_b32_e32 v58, v4
	v_mov_b32_e32 v59, v4
	v_mov_b32_e32 v60, v4
	v_mov_b32_e32 v61, v4
	v_mov_b32_e32 v62, v4
	v_mov_b32_e32 v63, v4
	v_mov_b32_e32 v64, v4
	v_mov_b32_e32 v65, v4
	v_mov_b32_e32 v66, v4
	v_mov_b32_e32 v67, v4
	v_readlane_b32 s22, v127, 2
	v_readlane_b32 s23, v127, 3
	v_readfirstlane_b32 s98, v76
	s_movk_i32 s99, 0x6000
	s_add_i32 s101, s98, s99
	s_mov_b32 m0, s101
	s_add_i32 s101, s101, 0x2000
	global_load_lds_dwordx4 v[0:1], off
	s_mov_b32 m0, s101
	s_add_i32 s101, s101, 0x2000
	global_load_lds_dwordx4 v[68:69], off
	s_mov_b32 m0, s101
	s_add_i32 s99, s99, 0x6000
	global_load_lds_dwordx4 v[70:71], off
	s_cmp_eq_u32 s99, 0x12000
	s_cselect_b32 s99, 0, s99
	v_lshl_add_u64 v[0:1], v[0:1], 0, 64
	v_lshl_add_u64 v[68:69], v[68:69], 0, 64
	v_lshl_add_u64 v[70:71], v[70:71], 0, 64
	s_add_i32 s101, s98, s99
	s_mov_b32 m0, s101
	s_add_i32 s101, s101, 0x2000
	global_load_lds_dwordx4 v[0:1], off
	s_mov_b32 m0, s101
	s_add_i32 s101, s101, 0x2000
	global_load_lds_dwordx4 v[68:69], off
	s_mov_b32 m0, s101
	s_add_i32 s99, s99, 0x6000
	global_load_lds_dwordx4 v[70:71], off
	s_cmp_eq_u32 s99, 0x12000
	s_cselect_b32 s99, 0, s99
	v_lshl_add_u64 v[0:1], v[0:1], 0, 64
	v_lshl_add_u64 v[68:69], v[68:69], 0, 64
	v_lshl_add_u64 v[70:71], v[70:71], 0, 64
	s_mov_b32 s100, 0
	s_waitcnt vmcnt(6)
	s_barrier
	v_or_b32_e32 v112, s100, v77
	v_add_u32_e32 v113, v112, v78
	v_add_u32_e32 v112, v112, v79
	ds_read_b128 v[80:83], v113 offset:16384
	ds_read_b128 v[84:87], v113 offset:17408
	ds_read_b128 v[88:91], v113 offset:18432
	ds_read_b128 v[92:95], v113 offset:19456
	ds_read_b128 v[96:99], v112
	ds_read_b128 v[100:103], v112 offset:1024
	ds_read_b128 v[104:107], v112 offset:2048
	ds_read_b128 v[108:111], v112 offset:3072
	s_add_i32 s100, s100, 0x6000
	s_cmp_eq_u32 s100, 0x12000
	s_cselect_b32 s100, 0, s100

; template <int MODE, bool SWAP, int MT>
; DI void gemm_tile(const int wv_, const Params& p, const u16* __restrict__ A, const u16* __restrict__ Bt, int brow, int bcol, char* smem, const float* gnext) {
;     ...
;   const int tid = tid_, wid = tid >> 6, lane = tid & 63, wr = wid >> 1, wc = wid & 1, fr = lane & 15, fq = lane >> 4;
;   f32x4 acc[MT][4];
; #pragma unroll
;   for (int m = 0; m < MT; ++m)
; #pragma unroll
;     for (int n = 0; n < 4; ++n) acc[m][n] = f32x4{0.f, 0.f, 0.f, 0.f};
;   const int ra = tid >> 2, cb = (tid & 3) * 8;
;   const u16* ga0 = A + (size_t)(brow + ra) * 1024 + cb;
;   const u16* ga1 = A + (size_t)(brow + 128 + ra) * 1024 + cb;
;   const u16* gb0 = Bt + (size_t)(bcol + ra) * 1024 + cb;
;   auto stage = [&](int t, int buf) {
;     char* sA = smem + buf * 24576; char* sB = sA + 16384;
;     if (MT >= 2 || tid < 256) __builtin_amdgcn_global_load_lds((const unsigned*)(ga0 + t * 32), (unsigned*)(sA + tid * 16), 16, 0, 0);
;     if (MT == 4) __builtin_amdgcn_global_load_lds((const unsigned*)(ga1 + t * 32), (unsigned*)(sA + 8192 + tid * 16), 16, 0, 0);
;     __builtin_amdgcn_global_load_lds((const unsigned*)(gb0 + t * 32), (unsigned*)(sB + tid * 16), 16, 0, 0);
;   };
;   stage(0, 0);
;   for (int t = 0; t < 32; ++t) {
;     asm volatile("s_waitcnt vmcnt(0)" ::: "memory");
;     __syncthreads();
;     if (t + 1 < 32) stage(t + 1, (t + 1) & 1);
;     const char* sA = smem + (t & 1) * 24576; const char* sB = sA + 16384;
;     bf16x8 Af[MT], Bf[4];
; #pragma unroll
;     for (int n = 0; n < 4; ++n) Bf[n] = *(const bf16x8*)(sB + (wc * 64 + n * 16 + fr) * 64 + fq * 16);
;     constexpr int MH = MT >= 2 ? MT / 2 : 1;
; #pragma unroll
;     for (int m = 0; m < MH; ++m) Af[m] = *(const bf16x8*)(sA + (wr * (16 * MT) + m * 16 + fr) * 64 + fq * 16);
.LBB0_88:
	s_and_b64 vcc, exec, s[0:1]
	s_cbranch_vccz .LBB0_83
	s_mov_b32 s1, 0
	v_readlane_b32 s20, v127, 0
	v_mbcnt_lo_u32_b32 v0, -1, s1
	v_mbcnt_hi_u32_b32 v0, -1, v0
	v_add_u32_e32 v12, s33, v0
	s_mov_b32 s1, s16
	v_ashrrev_i32_e32 v13, 2, v12
	v_add_u32_e32 v0, s18, v13
	s_mov_b32 s1, s17
	v_ashrrev_i32_e32 v1, 31, v0
	v_lshlrev_b64 v[4:5], 11, v[0:1]
	v_readlane_b32 s21, v127, 1
	v_lshlrev_b32_e32 v76, 4, v12
	v_lshrrev_b32_e32 v2, 8, v76
	v_sub_u32_e32 v2, 0, v2
	v_lshlrev_b32_e32 v2, 4, v2
	v_xor_b32_e32 v2, v2, v76
	v_and_b32_e32 v2, 48, v2
	v_lshl_add_u64 v[6:7], s[20:21], 0, v[4:5]
	v_add_u32_e32 v0, 0x80, v0
	v_readfirstlane_b32 s1, v76
	v_lshl_add_u64 v[6:7], v[6:7], 0, v[2:3]
	v_ashrrev_i32_e32 v1, 31, v0
	s_mov_b32 m0, s1
	v_lshlrev_b64 v[8:9], 11, v[0:1]
	global_load_lds_dwordx4 v[6:7], off
	v_add_u32_e32 v6, 0x2000, v76
	v_lshl_add_u64 v[0:1], s[20:21], 0, v[8:9]
	v_add_u32_e32 v10, s15, v13
	v_readfirstlane_b32 s1, v6
	v_lshl_add_u64 v[0:1], v[0:1], 0, v[2:3]
	v_ashrrev_i32_e32 v11, 31, v10
	s_mov_b32 m0, s1
	v_lshlrev_b64 v[10:11], 11, v[10:11]
	global_load_lds_dwordx4 v[0:1], off
	v_add_u32_e32 v0, 0x4000, v76
	v_lshl_add_u64 v[10:11], s[2:3], 0, v[10:11]
	v_readfirstlane_b32 s1, v0
	v_lshl_add_u64 v[10:11], v[10:11], 0, v[2:3]
	s_mov_b32 m0, s1
	v_and_b32_e32 v73, 15, v12
	global_load_lds_dwordx4 v[10:11], off
	v_readlane_b32 s20, v127, 22
	v_bfe_u32 v72, v12, 6, 1
	v_ashrrev_i32_e32 v74, 7, v12
	v_lshlrev_b32_e32 v0, 6, v73
	v_or_b32_e32 v4, v4, v2
	v_readlane_b32 s21, v127, 23
	v_lshl_or_b32 v78, v72, 12, v0
	v_lshl_or_b32 v79, v74, 12, v0
	v_lshl_add_u64 v[0:1], s[20:21], 0, v[4:5]
	v_add_u32_e32 v4, s12, v13
	v_subrev_u32_e32 v4, s19, v4
	v_ashrrev_i32_e32 v5, 31, v4
	v_lshlrev_b64 v[4:5], 11, v[4:5]
	v_or_b32_e32 v4, v4, v2
	v_bfe_u32 v75, v12, 4, 2
	v_or_b32_e32 v8, v8, v2
	v_lshl_add_u64 v[70:71], s[4:5], 0, v[4:5]
	v_mov_b32_e32 v4, 0
	s_mov_b32 s0, 0
	v_lshrrev_b32_e32 v77, 2, v73
	v_sub_u32_e32 v77, 0, v77
	v_xor_b32_e32 v77, v77, v75
	v_and_b32_e32 v77, 3, v77
	v_lshlrev_b32_e32 v77, 4, v77
	v_lshl_add_u64 v[68:69], s[20:21], 0, v[8:9]
	v_mov_b32_e32 v5, v4
	v_mov_b32_e32 v6, v4
	v_mov_b32_e32 v7, v4
	v_mov_b32_e32 v8, v4
	v_mov_b32_e32 v9, v4
	v_mov_b32_e32 v10, v4
	v_mov_b32_e32 v11, v4
	v_mov_b32_e32 v12, v4
	v_mov_b32_e32 v13, v4
	v_mov_b32_e32 v14, v4
	v_mov_b32_e32 v15, v4
	v_mov_b32_e32 v16, v4
	v_mov_b32_e32 v17, v4
	v_mov_b32_e32 v18, v4
	v_mov_b32_e32 v19, v4
	v_mov_b32_e32 v20, v4
	v_mov_b32_e32 v21, v4
	v_mov_b32_e32 v22, v4
	v_mov_b32_e32 v23, v4
	v_mov_b32_e32 v24, v4
	v_mov_b32_e32 v25, v4
	v_mov_b32_e32 v26, v4
	v_mov_b32_e32 v27, v4
	v_mov_b32_e32 v28, v4
	v_mov_b32_e32 v29, v4
	v_mov_b32_e32 v30, v4
	v_mov_b32_e32 v31, v4
	v_mov_b32_e32 v32, v4
	v_mov_b32_e32 v33, v4
	v_mov_b32_e32 v34, v4
	v_mov_b32_e32 v35, v4
	v_mov_b32_e32 v36, v4
	v_mov_b32_e32 v37, v4
	v_mov_b32_e32 v38, v4
	v_mov_b32_e32 v39, v4
	v_mov_b32_e32 v40, v4
	v_mov_b32_e32 v41, v4
	v_mov_b32_e32 v42, v4
	v_mov_b32_e32 v43, v4
	v_mov_b32_e32 v44, v4
	v_mov_b32_e32 v45, v4
	v_mov_b32_e32 v46, v4
	v_mov_b32_e32 v47, v4
	v_mov_b32_e32 v48, v4
	v_mov_b32_e32 v49, v4
	v_mov_b32_e32 v50, v4
	v_mov_b32_e32 v51, v4
	v_mov_b32_e32 v52, v4
	v_mov_b32_e32 v53, v4
	v_mov_b32_e32 v54, v4
	v_mov_b32_e32 v55, v4
	v_mov_b32_e32 v56, v4
	v_mov_b32_e32 v57, v4
	v_mov_b32_e32 v58, v4
	v_mov_b32_e32 v59, v4
	v_mov_b32_e32 v60, v4
	v_mov_b32_e32 v61, v4
	v_mov_b32_e32 v62, v4
	v_mov_b32_e32 v63, v4
	v_mov_b32_e32 v64, v4
	v_mov_b32_e32 v65, v4
	v_mov_b32_e32 v66, v4
	v_mov_b32_e32 v67, v4
	v_readlane_b32 s22, v127, 2
	v_readlane_b32 s23, v127, 3
	v_readfirstlane_b32 s98, v76
	s_movk_i32 s99, 0x6000
	s_add_i32 s101, s98, s99
	s_mov_b32 m0, s101
	s_add_i32 s101, s101, 0x2000
	global_load_lds_dwordx4 v[0:1], off
	s_mov_b32 m0, s101
	s_add_i32 s101, s101, 0x2000
	global_load_lds_dwordx4 v[68:69], off
	s_mov_b32 m0, s101
	s_add_i32 s99, s99, 0x6000
	global_load_lds_dwordx4 v[70:71], off
	s_cmp_eq_u32 s99, 0x12000
	s_cselect_b32 s99, 0, s99
	v_lshl_add_u64 v[0:1], v[0:1], 0, 64
	v_lshl_add_u64 v[68:69], v[68:69], 0, 64
	v_lshl_add_u64 v[70:71], v[70:71], 0, 64
	s_add_i32 s101, s98, s99
	s_mov_b32 m0, s101
	s_add_i32 s101, s101, 0x2000
	global_load_lds_dwordx4 v[0:1], off
	s_mov_b32 m0, s101
	s_add_i32 s101, s101, 0x2000
	global_load_lds_dwordx4 v[68:69], off
	s_mov_b32 m0, s101
	s_add_i32 s99, s99, 0x6000
	global_load_lds_dwordx4 v[70:71], off
	s_cmp_eq_u32 s99, 0x12000
	s_cselect_b32 s99, 0, s99
	v_lshl_add_u64 v[0:1], v[0:1], 0, 64
	v_lshl_add_u64 v[68:69], v[68:69], 0, 64
	v_lshl_add_u64 v[70:71], v[70:71], 0, 64
	s_mov_b32 s100, 0
	s_waitcnt vmcnt(6)
	s_barrier
	v_or_b32_e32 v112, s100, v77
	v_add_u32_e32 v113, v112, v78
	v_add_u32_e32 v112, v112, v79
	ds_read_b128 v[80:83], v113 offset:16384
	ds_read_b128 v[84:87], v113 offset:17408
	ds_read_b128 v[88:91], v113 offset:18432
	ds_read_b128 v[92:95], v113 offset:19456
	ds_read_b128 v[96:99], v112
	ds_read_b128 v[100:103], v112 offset:1024
	ds_read_b128 v[104:107], v112 offset:2048
	ds_read_b128 v[108:111], v112 offset:3072
	s_add_i32 s100, s100, 0x6000
	s_cmp_eq_u32 s100, 0x12000
	s_cselect_b32 s100, 0, s100

; template <int MODE, bool SWAP, int MT>
; DI void gemm_tile(const int wv_, const Params& p, const u16* __restrict__ A, const u16* __restrict__ Bt, int brow, int bcol, char* smem, const float* gnext) {
;     ...
;   const int tid = tid_, wid = tid >> 6, lane = tid & 63, wr = wid >> 1, wc = wid & 1, fr = lane & 15, fq = lane >> 4;
;   f32x4 acc[MT][4];
; #pragma unroll
;   for (int m = 0; m < MT; ++m)
; #pragma unroll
;     for (int n = 0; n < 4; ++n) acc[m][n] = f32x4{0.f, 0.f, 0.f, 0.f};
;   const int ra = tid >> 2, cb = (tid & 3) * 8;
;   const u16* ga0 = A + (size_t)(brow + ra) * 1024 + cb;
;   const u16* ga1 = A + (size_t)(brow + 128 + ra) * 1024 + cb;
;   const u16* gb0 = Bt + (size_t)(bcol + ra) * 1024 + cb;
;   auto stage = [&](int t, int buf) {
;     char* sA = smem + buf * 24576; char* sB = sA + 16384;
;     if (MT >= 2 || tid < 256) __builtin_amdgcn_global_load_lds((const unsigned*)(ga0 + t * 32), (unsigned*)(sA + tid * 16), 16, 0, 0);
;     if (MT == 4) __builtin_amdgcn_global_load_lds((const unsigned*)(ga1 + t * 32), (unsigned*)(sA + 8192 + tid * 16), 16, 0, 0);
;     __builtin_amdgcn_global_load_lds((const unsigned*)(gb0 + t * 32), (unsigned*)(sB + tid * 16), 16, 0, 0);
;   };
;   stage(0, 0);
;   for (int t = 0; t < 32; ++t) {
;     asm volatile("s_waitcnt vmcnt(0)" ::: "memory");
;     __syncthreads();
;     if (t + 1 < 32) stage(t + 1, (t + 1) & 1);
;     const char* sA = smem + (t & 1) * 24576; const char* sB = sA + 16384;
;     bf16x8 Af[MT], Bf[4];
; #pragma unroll
;     for (int n = 0; n < 4; ++n) Bf[n] = *(const bf16x8*)(sB + (wc * 64 + n * 16 + fr) * 64 + fq * 16);
;     constexpr int MH = MT >= 2 ? MT / 2 : 1;
; #pragma unroll
;     for (int m = 0; m < MH; ++m) Af[m] = *(const bf16x8*)(sA + (wr * (16 * MT) + m * 16 + fr) * 64 + fq * 16);
; template <int MODE>
; DI void phase_gemm(const int wv_, const Params& p, const u16* A, const u16* Bt, int NT, char* smem, const float* gnext) {
;     ...
;     int tm = tile / NT, tn = tile - tm * NT;
;     if (MODE == 1 && tn >= 20 && tn < 24) gemm_tile<1, false, 4>(wv_, p, A, Bt, tm * 256, tn * 128, smem, gnext);
;     else gemm_tile<MODE, true, 4>(wv_, p, A, Bt, tm * 256, tn * 128, smem, gnext);
.LBB0_372:
	s_mul_hi_i32 s0, s22, 0x3e0f83e1
	s_mov_b32 s7, 0
	s_lshr_b32 s1, s0, 31
	s_ashr_i32 s0, s0, 3
	s_add_i32 s6, s0, s1
	v_mbcnt_lo_u32_b32 v0, -1, s7
	v_mbcnt_hi_u32_b32 v0, -1, v0
	s_mul_i32 s0, s6, 0xffffffdf
	v_add_u32_e32 v2, s33, v0
	s_add_i32 s1, s0, s22
	s_lshl_b32 s0, s6, 8
	s_mov_b32 s7, s16
	v_ashrrev_i32_e32 v12, 2, v2
	v_add_u32_e32 v0, s0, v12
	s_mov_b32 s7, s17
	v_ashrrev_i32_e32 v1, 31, v0
	v_readlane_b32 s8, v127, 0
	v_lshlrev_b64 v[4:5], 11, v[0:1]
	v_readlane_b32 s9, v127, 1
	v_lshlrev_b32_e32 v76, 4, v2
	v_bfe_u32 v72, v2, 6, 1
	v_ashrrev_i32_e32 v74, 7, v2
	v_and_b32_e32 v75, 15, v2
	v_bfe_u32 v73, v2, 4, 2
	v_lshl_add_u64 v[6:7], s[8:9], 0, v[4:5]
	v_lshrrev_b32_e32 v2, 8, v76
	v_sub_u32_e32 v2, 0, v2
	v_lshlrev_b32_e32 v2, 4, v2
	v_xor_b32_e32 v2, v2, v76
	v_and_b32_e32 v2, 48, v2
	v_add_u32_e32 v0, 0x80, v0
	v_readfirstlane_b32 s7, v76
	v_lshl_add_u64 v[6:7], v[6:7], 0, v[2:3]
	v_ashrrev_i32_e32 v1, 31, v0
	s_mov_b32 m0, s7
	s_lshl_b32 s23, s1, 7
	v_lshlrev_b64 v[8:9], 11, v[0:1]
	global_load_lds_dwordx4 v[6:7], off
	v_add_u32_e32 v6, 0x2000, v76
	v_lshl_add_u64 v[0:1], s[8:9], 0, v[8:9]
	v_add_u32_e32 v10, s23, v12
	v_readfirstlane_b32 s7, v6
	v_lshl_add_u64 v[0:1], v[0:1], 0, v[2:3]
	v_ashrrev_i32_e32 v11, 31, v10
	s_mov_b32 m0, s7
	v_lshlrev_b64 v[10:11], 11, v[10:11]
	global_load_lds_dwordx4 v[0:1], off
	v_add_u32_e32 v0, 0x4000, v76
	v_lshl_add_u64 v[10:11], s[2:3], 0, v[10:11]
	v_readfirstlane_b32 s7, v0
	v_lshl_add_u64 v[10:11], v[10:11], 0, v[2:3]
	s_mov_b32 m0, s7
	v_readlane_b32 s8, v127, 22
	global_load_lds_dwordx4 v[10:11], off
	v_lshlrev_b32_e32 v0, 6, v75
	v_or_b32_e32 v4, v4, v2
	v_readlane_b32 s9, v127, 23
	v_lshl_or_b32 v78, v72, 12, v0
	v_lshl_or_b32 v79, v74, 12, v0
	v_lshl_add_u64 v[0:1], s[8:9], 0, v[4:5]
	v_add_u32_e32 v4, s20, v12
	s_mulk_i32 s6, 0x1080
	v_subrev_u32_e32 v4, s6, v4
	v_ashrrev_i32_e32 v5, 31, v4
	v_lshlrev_b64 v[4:5], 11, v[4:5]
	v_or_b32_e32 v4, v4, v2
	v_or_b32_e32 v8, v8, v2
	v_lshl_add_u64 v[70:71], s[4:5], 0, v[4:5]
	v_mov_b32_e32 v4, 0
	s_mov_b32 s1, 0
	v_lshrrev_b32_e32 v77, 2, v75
	v_sub_u32_e32 v77, 0, v77
	v_xor_b32_e32 v77, v77, v73
	v_and_b32_e32 v77, 3, v77
	v_lshlrev_b32_e32 v77, 4, v77
	v_lshl_add_u64 v[68:69], s[8:9], 0, v[8:9]
	v_mov_b32_e32 v5, v4
	v_mov_b32_e32 v6, v4
	v_mov_b32_e32 v7, v4
	v_mov_b32_e32 v8, v4
	v_mov_b32_e32 v9, v4
	v_mov_b32_e32 v10, v4
	v_mov_b32_e32 v11, v4
	v_mov_b32_e32 v12, v4
	v_mov_b32_e32 v13, v4
	v_mov_b32_e32 v14, v4
	v_mov_b32_e32 v15, v4
	v_mov_b32_e32 v16, v4
	v_mov_b32_e32 v17, v4
	v_mov_b32_e32 v18, v4
	v_mov_b32_e32 v19, v4
	v_mov_b32_e32 v20, v4
	v_mov_b32_e32 v21, v4
	v_mov_b32_e32 v22, v4
	v_mov_b32_e32 v23, v4
	v_mov_b32_e32 v24, v4
	v_mov_b32_e32 v25, v4
	v_mov_b32_e32 v26, v4
	v_mov_b32_e32 v27, v4
	v_mov_b32_e32 v28, v4
	v_mov_b32_e32 v29, v4
	v_mov_b32_e32 v30, v4
	v_mov_b32_e32 v31, v4
	v_mov_b32_e32 v32, v4
	v_mov_b32_e32 v33, v4
	v_mov_b32_e32 v34, v4
	v_mov_b32_e32 v35, v4
	v_mov_b32_e32 v44, v4
	v_mov_b32_e32 v45, v4
	v_mov_b32_e32 v46, v4
	v_mov_b32_e32 v47, v4
	v_mov_b32_e32 v36, v4
	v_mov_b32_e32 v37, v4
	v_mov_b32_e32 v38, v4
	v_mov_b32_e32 v39, v4
	v_mov_b32_e32 v40, v4
	v_mov_b32_e32 v41, v4
	v_mov_b32_e32 v42, v4
	v_mov_b32_e32 v43, v4
	v_mov_b32_e32 v48, v4
	v_mov_b32_e32 v49, v4
	v_mov_b32_e32 v50, v4
	v_mov_b32_e32 v51, v4
	v_mov_b32_e32 v52, v4
	v_mov_b32_e32 v53, v4
	v_mov_b32_e32 v54, v4
	v_mov_b32_e32 v55, v4
	v_mov_b32_e32 v56, v4
	v_mov_b32_e32 v57, v4
	v_mov_b32_e32 v58, v4
	v_mov_b32_e32 v59, v4
	v_mov_b32_e32 v60, v4
	v_mov_b32_e32 v61, v4
	v_mov_b32_e32 v62, v4
	v_mov_b32_e32 v63, v4
	v_mov_b32_e32 v64, v4
	v_mov_b32_e32 v65, v4
	v_mov_b32_e32 v66, v4
	v_mov_b32_e32 v67, v4
	v_readlane_b32 s10, v127, 2
	v_readlane_b32 s11, v127, 3
	v_readfirstlane_b32 s98, v76
	s_movk_i32 s99, 0x6000
	s_add_i32 s101, s98, s99
	s_mov_b32 m0, s101
	s_add_i32 s101, s101, 0x2000
	global_load_lds_dwordx4 v[0:1], off
	s_mov_b32 m0, s101
	s_add_i32 s101, s101, 0x2000
	global_load_lds_dwordx4 v[68:69], off
	s_mov_b32 m0, s101
	s_add_i32 s99, s99, 0x6000
	global_load_lds_dwordx4 v[70:71], off
	s_cmp_eq_u32 s99, 0x12000
	s_cselect_b32 s99, 0, s99
	v_lshl_add_u64 v[0:1], v[0:1], 0, 64
	v_lshl_add_u64 v[68:69], v[68:69], 0, 64
	v_lshl_add_u64 v[70:71], v[70:71], 0, 64
	s_add_i32 s101, s98, s99
	s_mov_b32 m0, s101
	s_add_i32 s101, s101, 0x2000
	global_load_lds_dwordx4 v[0:1], off
	s_mov_b32 m0, s101
	s_add_i32 s101, s101, 0x2000
	global_load_lds_dwordx4 v[68:69], off
	s_mov_b32 m0, s101
	s_add_i32 s99, s99, 0x6000
	global_load_lds_dwordx4 v[70:71], off
	s_cmp_eq_u32 s99, 0x12000
	s_cselect_b32 s99, 0, s99
	v_lshl_add_u64 v[0:1], v[0:1], 0, 64
	v_lshl_add_u64 v[68:69], v[68:69], 0, 64
	v_lshl_add_u64 v[70:71], v[70:71], 0, 64
	s_mov_b32 s100, 0
	s_waitcnt vmcnt(6)
	s_barrier
	v_or_b32_e32 v112, s100, v77
	v_add_u32_e32 v113, v112, v78
	v_add_u32_e32 v112, v112, v79
	ds_read_b128 v[80:83], v113 offset:16384
	ds_read_b128 v[84:87], v113 offset:17408
	ds_read_b128 v[88:91], v113 offset:18432
	ds_read_b128 v[92:95], v113 offset:19456
	ds_read_b128 v[96:99], v112
	ds_read_b128 v[100:103], v112 offset:1024
	ds_read_b128 v[104:107], v112 offset:2048
	ds_read_b128 v[108:111], v112 offset:3072
	s_add_i32 s100, s100, 0x6000
	s_cmp_eq_u32 s100, 0x12000
	s_cselect_b32 s100, 0, s100

; template <int MODE, bool SWAP, int MT>
; DI void gemm_tile(const int wv_, const Params& p, const u16* __restrict__ A, const u16* __restrict__ Bt, int brow, int bcol, char* smem, const float* gnext) {
;     ...
;   const int tid = tid_, wid = tid >> 6, lane = tid & 63, wr = wid >> 1, wc = wid & 1, fr = lane & 15, fq = lane >> 4;
;   f32x4 acc[MT][4];
; #pragma unroll
;   for (int m = 0; m < MT; ++m)
; #pragma unroll
;     for (int n = 0; n < 4; ++n) acc[m][n] = f32x4{0.f, 0.f, 0.f, 0.f};
;   const int ra = tid >> 2, cb = (tid & 3) * 8;
;   const u16* ga0 = A + (size_t)(brow + ra) * 1024 + cb;
;   const u16* ga1 = A + (size_t)(brow + 128 + ra) * 1024 + cb;
;   const u16* gb0 = Bt + (size_t)(bcol + ra) * 1024 + cb;
;   auto stage = [&](int t, int buf) {
;     char* sA = smem + buf * 24576; char* sB = sA + 16384;
;     if (MT >= 2 || tid < 256) __builtin_amdgcn_global_load_lds((const unsigned*)(ga0 + t * 32), (unsigned*)(sA + tid * 16), 16, 0, 0);
;     if (MT == 4) __builtin_amdgcn_global_load_lds((const unsigned*)(ga1 + t * 32), (unsigned*)(sA + 8192 + tid * 16), 16, 0, 0);
;     __builtin_amdgcn_global_load_lds((const unsigned*)(gb0 + t * 32), (unsigned*)(sB + tid * 16), 16, 0, 0);
;   };
;   stage(0, 0);
;   for (int t = 0; t < 32; ++t) {
;     asm volatile("s_waitcnt vmcnt(0)" ::: "memory");
;     __syncthreads();
;     if (t + 1 < 32) stage(t + 1, (t + 1) & 1);
;     const char* sA = smem + (t & 1) * 24576; const char* sB = sA + 16384;
;     bf16x8 Af[MT], Bf[4];
; #pragma unroll
;     for (int n = 0; n < 4; ++n) Bf[n] = *(const bf16x8*)(sB + (wc * 64 + n * 16 + fr) * 64 + fq * 16);
;     constexpr int MH = MT >= 2 ? MT / 2 : 1;
; #pragma unroll
;     for (int m = 0; m < MH; ++m) Af[m] = *(const bf16x8*)(sA + (wr * (16 * MT) + m * 16 + fr) * 64 + fq * 16);
; template <int MODE>
; DI void phase_gemm(const int wv_, const Params& p, const u16* A, const u16* Bt, int NT, char* smem, const float* gnext) {
;     ...
;     int tm = tile / NT, tn = tile - tm * NT;
;     if (MODE == 1 && tn >= 20 && tn < 24) gemm_tile<1, false, 4>(wv_, p, A, Bt, tm * 256, tn * 128, smem, gnext);
;     else gemm_tile<MODE, true, 4>(wv_, p, A, Bt, tm * 256, tn * 128, smem, gnext);
.LBB0_828:
	s_ashr_i32 s0, s28, 31
	s_mov_b32 s3, 0
	s_lshr_b32 s0, s0, 29
	s_add_i32 s0, s28, s0
	v_mbcnt_lo_u32_b32 v0, -1, s3
	v_mbcnt_hi_u32_b32 v0, -1, v0
	s_ashr_i32 s1, s0, 3
	v_add_u32_e32 v77, s33, v0
	s_lshl_b32 s0, s1, 8
	s_mov_b32 s3, s16
	v_ashrrev_i32_e32 v12, 2, v77
	v_add_u32_e32 v0, s0, v12
	s_mov_b32 s3, s17
	s_waitcnt lgkmcnt(0)
	v_ashrrev_i32_e32 v1, 31, v0
	v_lshlrev_b64 v[4:5], 11, v[0:1]
	v_lshlrev_b32_e32 v74, 4, v77
	v_lshl_add_u64 v[6:7], s[50:51], 0, v[4:5]
	v_lshrrev_b32_e32 v2, 8, v74
	v_sub_u32_e32 v2, 0, v2
	v_lshlrev_b32_e32 v2, 4, v2
	v_xor_b32_e32 v2, v2, v74
	v_and_b32_e32 v2, 48, v2
	v_add_u32_e32 v0, 0x80, v0
	v_readfirstlane_b32 s3, v74
	s_lshl_b32 s2, s1, 10
	s_lshl_b32 s1, s28, 7
	v_lshl_add_u64 v[6:7], v[6:7], 0, v[2:3]
	v_ashrrev_i32_e32 v1, 31, v0
	s_mov_b32 m0, s3
	s_sub_i32 s12, s1, s2
	v_lshlrev_b64 v[8:9], 11, v[0:1]
	global_load_lds_dwordx4 v[6:7], off
	v_add_u32_e32 v6, 0x2000, v74
	v_lshl_add_u64 v[0:1], s[50:51], 0, v[8:9]
	v_add_u32_e32 v10, s12, v12
	v_readfirstlane_b32 s3, v6
	v_lshl_add_u64 v[0:1], v[0:1], 0, v[2:3]
	v_ashrrev_i32_e32 v11, 31, v10
	s_mov_b32 m0, s3
	v_lshlrev_b64 v[10:11], 11, v[10:11]
	global_load_lds_dwordx4 v[0:1], off
	v_add_u32_e32 v0, 0x4000, v74
	v_lshl_add_u64 v[10:11], s[6:7], 0, v[10:11]
	v_readfirstlane_b32 s3, v0
	v_lshl_add_u64 v[10:11], v[10:11], 0, v[2:3]
	s_mov_b32 m0, s3
	v_and_b32_e32 v73, 15, v77
	global_load_lds_dwordx4 v[10:11], off
	v_readlane_b32 s4, v127, 28
	v_bfe_u32 v76, v77, 6, 1
	v_ashrrev_i32_e32 v72, 7, v77
	v_lshlrev_b32_e32 v0, 6, v73
	v_or_b32_e32 v4, v4, v2
	v_readlane_b32 s5, v127, 29
	v_lshl_or_b32 v78, v76, 12, v0
	v_lshl_or_b32 v79, v72, 12, v0
	v_lshl_add_u64 v[0:1], s[4:5], 0, v[4:5]
	v_add_u32_e32 v4, s23, v12
	v_subrev_u32_e32 v4, s2, v4
	v_ashrrev_i32_e32 v5, 31, v4
	v_lshlrev_b64 v[4:5], 11, v[4:5]
	v_readlane_b32 s2, v127, 30
	v_or_b32_e32 v4, v4, v2
	v_readlane_b32 s3, v127, 31
	v_or_b32_e32 v8, v8, v2
	s_mov_b32 s1, 0
	v_lshl_add_u64 v[70:71], s[2:3], 0, v[4:5]
	v_mov_b32_e32 v4, 0
	v_lshrrev_b32_e32 v75, 2, v73
	v_sub_u32_e32 v75, 0, v75
	v_lshlrev_b32_e32 v75, 4, v75
	v_xor_b32_e32 v75, v75, v77
	v_and_b32_e32 v75, 48, v75
	v_lshl_add_u64 v[68:69], s[4:5], 0, v[8:9]
	v_mov_b32_e32 v5, v4
	v_mov_b32_e32 v6, v4
	v_mov_b32_e32 v7, v4
	v_mov_b32_e32 v8, v4
	v_mov_b32_e32 v9, v4
	v_mov_b32_e32 v10, v4
	v_mov_b32_e32 v11, v4
	v_mov_b32_e32 v12, v4
	v_mov_b32_e32 v13, v4
	v_mov_b32_e32 v14, v4
	v_mov_b32_e32 v15, v4
	v_mov_b32_e32 v16, v4
	v_mov_b32_e32 v17, v4
	v_mov_b32_e32 v18, v4
	v_mov_b32_e32 v19, v4
	v_mov_b32_e32 v20, v4
	v_mov_b32_e32 v21, v4
	v_mov_b32_e32 v22, v4
	v_mov_b32_e32 v23, v4
	v_mov_b32_e32 v24, v4
	v_mov_b32_e32 v25, v4
	v_mov_b32_e32 v26, v4
	v_mov_b32_e32 v27, v4
	v_mov_b32_e32 v28, v4
	v_mov_b32_e32 v29, v4
	v_mov_b32_e32 v30, v4
	v_mov_b32_e32 v31, v4
	v_mov_b32_e32 v32, v4
	v_mov_b32_e32 v33, v4
	v_mov_b32_e32 v34, v4
	v_mov_b32_e32 v35, v4
	v_mov_b32_e32 v36, v4
	v_mov_b32_e32 v37, v4
	v_mov_b32_e32 v38, v4
	v_mov_b32_e32 v39, v4
	v_mov_b32_e32 v40, v4
	v_mov_b32_e32 v41, v4
	v_mov_b32_e32 v42, v4
	v_mov_b32_e32 v43, v4
	v_mov_b32_e32 v44, v4
	v_mov_b32_e32 v45, v4
	v_mov_b32_e32 v46, v4
	v_mov_b32_e32 v47, v4
	v_mov_b32_e32 v48, v4
	v_mov_b32_e32 v49, v4
	v_mov_b32_e32 v50, v4
	v_mov_b32_e32 v51, v4
	v_mov_b32_e32 v52, v4
	v_mov_b32_e32 v53, v4
	v_mov_b32_e32 v54, v4
	v_mov_b32_e32 v55, v4
	v_mov_b32_e32 v56, v4
	v_mov_b32_e32 v57, v4
	v_mov_b32_e32 v58, v4
	v_mov_b32_e32 v59, v4
	v_mov_b32_e32 v60, v4
	v_mov_b32_e32 v61, v4
	v_mov_b32_e32 v62, v4
	v_mov_b32_e32 v63, v4
	v_mov_b32_e32 v64, v4
	v_mov_b32_e32 v65, v4
	v_mov_b32_e32 v66, v4
	v_mov_b32_e32 v67, v4
	v_readfirstlane_b32 s98, v74
	s_movk_i32 s99, 0x6000
	s_add_i32 s101, s98, s99
	s_mov_b32 m0, s101
	s_add_i32 s101, s101, 0x2000
	global_load_lds_dwordx4 v[0:1], off
	s_mov_b32 m0, s101
	s_add_i32 s101, s101, 0x2000
	global_load_lds_dwordx4 v[68:69], off
	s_mov_b32 m0, s101
	s_add_i32 s99, s99, 0x6000
	global_load_lds_dwordx4 v[70:71], off
	s_cmp_eq_u32 s99, 0x12000
	s_cselect_b32 s99, 0, s99
	v_lshl_add_u64 v[0:1], v[0:1], 0, 64
	v_lshl_add_u64 v[68:69], v[68:69], 0, 64
	v_lshl_add_u64 v[70:71], v[70:71], 0, 64
	s_add_i32 s101, s98, s99
	s_mov_b32 m0, s101
	s_add_i32 s101, s101, 0x2000
	global_load_lds_dwordx4 v[0:1], off
	s_mov_b32 m0, s101
	s_add_i32 s101, s101, 0x2000
	global_load_lds_dwordx4 v[68:69], off
	s_mov_b32 m0, s101
	s_add_i32 s99, s99, 0x6000
	global_load_lds_dwordx4 v[70:71], off
	s_cmp_eq_u32 s99, 0x12000
	s_cselect_b32 s99, 0, s99
	v_lshl_add_u64 v[0:1], v[0:1], 0, 64
	v_lshl_add_u64 v[68:69], v[68:69], 0, 64
	v_lshl_add_u64 v[70:71], v[70:71], 0, 64
	s_mov_b32 s100, 0
	s_waitcnt vmcnt(6)
	s_barrier
	v_or_b32_e32 v112, s100, v75
	v_add_u32_e32 v113, v112, v78
	v_add_u32_e32 v112, v112, v79
	ds_read_b128 v[80:83], v113 offset:16384
	ds_read_b128 v[84:87], v113 offset:17408
	ds_read_b128 v[88:91], v113 offset:18432
	ds_read_b128 v[92:95], v113 offset:19456
	ds_read_b128 v[96:99], v112
	ds_read_b128 v[100:103], v112 offset:1024
	ds_read_b128 v[104:107], v112 offset:2048
	ds_read_b128 v[108:111], v112 offset:3072
	s_add_i32 s100, s100, 0x6000
	s_cmp_eq_u32 s100, 0x12000
	s_cselect_b32 s100, 0, s100
